# halfq MoBA/FoX items: the two 32-key sub-tiles of tile A fused (QK of one under the softmax of the other)
# speedup vs baseline: 1.0194x; 1.0110x over previous
; #define LAS __attribute__((address_space(3)))
; DI float ex2(float x) { return __builtin_amdgcn_exp2f(x); }
; template <int MODE>
; DI void sub_tile(const bf16x8 (&kf)[4], const bf16x8 (&vf)[2][2], const bf16x8 (&qf)[4], f32x16& o0, f32x16& o1, float& l, bool diag, float offs, float fm, const LAS float* fsp, int r, int h) {
;     ...
;         x = qk_tile(kf, qf);
; #pragma unroll
;         for (int g = 0; g < 4; ++g) {
;             const f32x4 fs = *(const LAS f32x4*)(fsp + 16 * (g >> 1) + 8 * h + 4 * (g & 1));
; #pragma unroll
;             for (int e = 0; e < 4; ++e) p[4 * g + e] = ex2(x[4 * g + e] + (fm - fs[e]));
;         }
;     }
;     if (diag) {
; #pragma unroll
;         for (int i = 0; i < 16; ++i) if (kidx(i, h) > r) p[i] = 0.f;
;     }
; #pragma unroll
;     for (int i = 0; i < 16; ++i) l += p[i];
;     pv_tile(o0, o1, vf, p);
; template <int MODE>
; DI void attn_wg2_item(const bf16_t* Qm, const bf16_t* Km, const bf16_t* Vtm, const float* Fb, const float* KMPb, const bf16_t* G, bf16_t* Y, int bh, int qb2, int halfq, int mixer, float Mb, LAS unsigned char* lds, int tid, int wave, int lane) {
;     ...
;                 bf16x8 kf[4], vf[2][2];
; #pragma unroll
;                 for (int sp = 0; sp < 4; ++sp) kf[sp] = *(LAS bf16x8*)(lb + kra + kk * 32 * 144 + sp * 32);
; #pragma unroll
;                 for (int dd = 0; dd < 2; ++dd)
; #pragma unroll
;                     for (int s = 0; s < 2; ++s) vf[dd][s] = *(LAS bf16x8*)(lb + vra + dd * 32 * 144 + kk * 64 + s * 32);
;                 float offA = mb2, offB = mb2;
;                 if (MODE == 2) { offA = ((nb == qblkA) || ((selA >> nb) & 1u)) ? mb2 : NEGI; offB = ((nb == qblkB) || ((selB >> nb) & 1u)) ? mb2 : NEGI; }
;                 const LAS float* fsp = (const LAS float*)(lb + AW_F) + kk * 32;
;                 if (actA) sub_tile<MODE>(kf, vf, qfA, oA0, oA1, lA, tau == qtA, offA, fmA, fsp, r, h);
;                 if (actB) sub_tile<MODE>(kf, vf, qfB, oB0, oB1, lB, tau == qtB, offB, fmB, fsp, r, h);
.LBB0_331:
	s_mul_i32 s5, s85, 0x4900
	s_add_i32 s50, s5, 0
	s_lshl_b32 s5, s64, 1
	s_cmp_lt_i32 s5, s69
	s_cselect_b64 s[66:67], -1, 0
	s_cmp_lt_i32 s5, s84
	s_cselect_b64 s[64:65], -1, 0
	v_add_u32_e32 v0, s50, v192
	v_add_u32_e32 v15, s50, v196
	s_or_b64 s[78:79], s[66:67], s[64:65]
	s_andn2_b64 vcc, exec, s[78:79]
	v_add_u32_e32 v14, v0, v194
	v_add_u32_e32 v0, v15, v194
	s_cbranch_vccnz .LBB0_340
	ds_read_b128 v[144:147], v14 offset:4608
	ds_read_b128 v[148:151], v14 offset:4640
	ds_read_b128 v[152:155], v14 offset:4672
	ds_read_b128 v[156:159], v14 offset:4704
	ds_read_b128 v[140:143], v0 offset:9280
	ds_read_b128 v[136:139], v0 offset:9312
	ds_read_b128 v[132:135], v0 offset:13888
	ds_read_b128 v[128:131], v0 offset:13920
	s_cmp_lt_i32 s84, 0
	s_cbranch_scc0 .Lfox_ns1
	s_and_b64 s[78:79], s[66:67], exec
	s_cbranch_scc0 .Lfox_ns1
	s_or_b32 s78, s5, 1
	s_cmp_lt_i32 s78, s69
	s_cbranch_scc0 .Lfox_ns1
	v_add_u32_e32 v179, s50, v197
	ds_read_b128 v[200:203], v179 offset:18560
	ds_read_b128 v[204:207], v179 offset:18576
	ds_read_b128 v[208:211], v179 offset:18624
	ds_read_b128 v[212:215], v179 offset:18640
	ds_read_b128 v[236:239], v179 offset:18432
	ds_read_b128 v[240:243], v179 offset:18448
	ds_read_b128 v[244:247], v179 offset:18496
	ds_read_b128 v[248:251], v179 offset:18512
	s_waitcnt lgkmcnt(4)
	v_sub_f32_e32 v80, v188, v200
	v_sub_f32_e32 v81, v188, v201
	v_sub_f32_e32 v82, v188, v202
	v_sub_f32_e32 v83, v188, v203
	v_sub_f32_e32 v84, v188, v204
	v_sub_f32_e32 v85, v188, v205
	v_sub_f32_e32 v86, v188, v206
	v_sub_f32_e32 v87, v188, v207
	v_sub_f32_e32 v88, v188, v208
	v_sub_f32_e32 v89, v188, v209
	v_sub_f32_e32 v90, v188, v210
	v_sub_f32_e32 v91, v188, v211
	v_sub_f32_e32 v92, v188, v212
	v_sub_f32_e32 v93, v188, v213
	v_sub_f32_e32 v94, v188, v214
	v_sub_f32_e32 v95, v188, v215
	ds_read_b128 v[200:203], v0 offset:9216
	ds_read_b128 v[204:207], v0 offset:9248
	ds_read_b128 v[208:211], v0 offset:13824
	ds_read_b128 v[212:215], v0 offset:13856
	s_setprio 1
	v_mfma_f32_32x32x16_bf16 v[80:95], v[144:147], v[96:99], v[80:95]
	v_mfma_f32_32x32x16_bf16 v[80:95], v[148:151], v[100:103], v[80:95]
	v_mfma_f32_32x32x16_bf16 v[80:95], v[152:155], v[104:107], v[80:95]
	v_mfma_f32_32x32x16_bf16 v[80:95], v[156:159], v[108:111], v[80:95]
	s_setprio 0
	s_waitcnt lgkmcnt(4)
	v_sub_f32_e32 v220, v188, v236
	v_sub_f32_e32 v221, v188, v237
	v_sub_f32_e32 v222, v188, v238
	v_sub_f32_e32 v223, v188, v239
	v_sub_f32_e32 v224, v188, v240
	v_sub_f32_e32 v225, v188, v241
	v_sub_f32_e32 v226, v188, v242
	v_sub_f32_e32 v227, v188, v243
	v_sub_f32_e32 v228, v188, v244
	v_sub_f32_e32 v229, v188, v245
	v_sub_f32_e32 v230, v188, v246
	v_sub_f32_e32 v231, v188, v247
	v_sub_f32_e32 v232, v188, v248
	v_sub_f32_e32 v233, v188, v249
	v_sub_f32_e32 v234, v188, v250
	v_sub_f32_e32 v235, v188, v251
	ds_read_b128 v[144:147], v14
	ds_read_b128 v[148:151], v14 offset:32
	ds_read_b128 v[152:155], v14 offset:64
	ds_read_b128 v[156:159], v14 offset:96
	v_exp_f32_e32 v80, v80
	v_exp_f32_e32 v81, v81
	v_exp_f32_e32 v82, v82
	v_exp_f32_e32 v83, v83
	v_exp_f32_e32 v84, v84
	v_exp_f32_e32 v85, v85
	v_exp_f32_e32 v86, v86
	v_exp_f32_e32 v87, v87
	v_exp_f32_e32 v88, v88
	v_exp_f32_e32 v89, v89
	v_exp_f32_e32 v90, v90
	v_exp_f32_e32 v91, v91
	v_exp_f32_e32 v92, v92
	v_exp_f32_e32 v93, v93
	v_exp_f32_e32 v94, v94
	v_exp_f32_e32 v95, v95
	s_waitcnt lgkmcnt(0)
	s_setprio 1
	v_mfma_f32_32x32x16_bf16 v[220:235], v[144:147], v[96:99], v[220:235]
	v_mfma_f32_32x32x16_bf16 v[220:235], v[148:151], v[100:103], v[220:235]
	v_mfma_f32_32x32x16_bf16 v[220:235], v[152:155], v[104:107], v[220:235]
	v_mfma_f32_32x32x16_bf16 v[220:235], v[156:159], v[108:111], v[220:235]
	s_setprio 0
	v_add_f32_e32 v198, v80, v198
	v_add_f32_e32 v198, v81, v198
	v_add_f32_e32 v198, v82, v198
	v_add_f32_e32 v198, v83, v198
	v_add_f32_e32 v198, v84, v198
	v_add_f32_e32 v198, v85, v198
	v_add_f32_e32 v198, v86, v198
	v_add_f32_e32 v198, v87, v198
	v_add_f32_e32 v198, v88, v198
	v_add_f32_e32 v198, v89, v198
	v_add_f32_e32 v198, v90, v198
	v_add_f32_e32 v198, v91, v198
	v_add_f32_e32 v198, v92, v198
	v_add_f32_e32 v198, v93, v198
	v_add_f32_e32 v198, v94, v198
	v_add_f32_e32 v198, v95, v198
	v_cvt_pk_bf16_f32 v80, v80, v81
	v_cvt_pk_bf16_f32 v81, v82, v83
	v_cvt_pk_bf16_f32 v82, v84, v85
	v_cvt_pk_bf16_f32 v83, v86, v87
	v_cvt_pk_bf16_f32 v84, v88, v89
	v_cvt_pk_bf16_f32 v85, v90, v91
	v_cvt_pk_bf16_f32 v86, v92, v93
	v_cvt_pk_bf16_f32 v87, v94, v95
	s_setprio 1
	v_mfma_f32_32x32x16_bf16 v[64:79], v[140:143], v[80:83], v[64:79]
	v_exp_f32_e32 v220, v220
	v_exp_f32_e32 v221, v221
	v_exp_f32_e32 v222, v222
	v_exp_f32_e32 v223, v223
	v_mfma_f32_32x32x16_bf16 v[48:63], v[132:135], v[80:83], v[48:63]
	v_exp_f32_e32 v224, v224
	v_exp_f32_e32 v225, v225
	v_exp_f32_e32 v226, v226
	v_exp_f32_e32 v227, v227
	v_mfma_f32_32x32x16_bf16 v[64:79], v[136:139], v[84:87], v[64:79]
	v_exp_f32_e32 v228, v228
	v_exp_f32_e32 v229, v229
	v_exp_f32_e32 v230, v230
	v_exp_f32_e32 v231, v231
	v_mfma_f32_32x32x16_bf16 v[48:63], v[128:131], v[84:87], v[48:63]
	v_exp_f32_e32 v232, v232
	v_exp_f32_e32 v233, v233
	v_exp_f32_e32 v234, v234
	v_exp_f32_e32 v235, v235
	s_setprio 0
	v_add_f32_e32 v198, v220, v198
	v_add_f32_e32 v198, v221, v198
	v_add_f32_e32 v198, v222, v198
	v_add_f32_e32 v198, v223, v198
	v_add_f32_e32 v198, v224, v198
	v_add_f32_e32 v198, v225, v198
	v_add_f32_e32 v198, v226, v198
	v_add_f32_e32 v198, v227, v198
	v_add_f32_e32 v198, v228, v198
	v_add_f32_e32 v198, v229, v198
	v_add_f32_e32 v198, v230, v198
	v_add_f32_e32 v198, v231, v198
	v_add_f32_e32 v198, v232, v198
	v_add_f32_e32 v198, v233, v198
	v_add_f32_e32 v198, v234, v198
	v_add_f32_e32 v198, v235, v198
	v_cvt_pk_bf16_f32 v220, v220, v221
	v_cvt_pk_bf16_f32 v221, v222, v223
	v_cvt_pk_bf16_f32 v222, v224, v225
	v_cvt_pk_bf16_f32 v223, v226, v227
	v_cvt_pk_bf16_f32 v224, v228, v229
	v_cvt_pk_bf16_f32 v225, v230, v231
	v_cvt_pk_bf16_f32 v226, v232, v233
	v_cvt_pk_bf16_f32 v227, v234, v235
	s_setprio 1
	v_mfma_f32_32x32x16_bf16 v[64:79], v[200:203], v[220:223], v[64:79]
	v_mfma_f32_32x32x16_bf16 v[48:63], v[208:211], v[220:223], v[48:63]
	v_mfma_f32_32x32x16_bf16 v[64:79], v[204:207], v[224:227], v[64:79]
	v_mfma_f32_32x32x16_bf16 v[48:63], v[212:215], v[224:227], v[48:63]
	s_setprio 0
	s_branch .LBB0_349
; #define LAS __attribute__((address_space(3)))
; DI float ex2(float x) { return __builtin_amdgcn_exp2f(x); }
; template <int MODE>
; DI void sub_tile(const bf16x8 (&kf)[4], const bf16x8 (&vf)[2][2], const bf16x8 (&qf)[4], f32x16& o0, f32x16& o1, float& l, bool diag, float offs, float fm, const LAS float* fsp, int r, int h) {
;     ...
;         x = qk_tile(kf, qf);
; #pragma unroll
;         for (int g = 0; g < 4; ++g) {
;             const f32x4 fs = *(const LAS f32x4*)(fsp + 16 * (g >> 1) + 8 * h + 4 * (g & 1));
; #pragma unroll
;             for (int e = 0; e < 4; ++e) p[4 * g + e] = ex2(x[4 * g + e] + (fm - fs[e]));
;         }
;     }
;     if (diag) {
; #pragma unroll
;         for (int i = 0; i < 16; ++i) if (kidx(i, h) > r) p[i] = 0.f;
;     }
; #pragma unroll
;     for (int i = 0; i < 16; ++i) l += p[i];
;     pv_tile(o0, o1, vf, p);
; template <int MODE>
; DI void attn_wg2_item(const bf16_t* Qm, const bf16_t* Km, const bf16_t* Vtm, const float* Fb, const float* KMPb, const bf16_t* G, bf16_t* Y, int bh, int qb2, int halfq, int mixer, float Mb, LAS unsigned char* lds, int tid, int wave, int lane) {
;     ...
;                 bf16x8 kf[4], vf[2][2];
; #pragma unroll
;                 for (int sp = 0; sp < 4; ++sp) kf[sp] = *(LAS bf16x8*)(lb + kra + kk * 32 * 144 + sp * 32);
; #pragma unroll
;                 for (int dd = 0; dd < 2; ++dd)
; #pragma unroll
;                     for (int s = 0; s < 2; ++s) vf[dd][s] = *(LAS bf16x8*)(lb + vra + dd * 32 * 144 + kk * 64 + s * 32);
;                 float offA = mb2, offB = mb2;
;                 if (MODE == 2) { offA = ((nb == qblkA) || ((selA >> nb) & 1u)) ? mb2 : NEGI; offB = ((nb == qblkB) || ((selB >> nb) & 1u)) ? mb2 : NEGI; }
;                 const LAS float* fsp = (const LAS float*)(lb + AW_F) + kk * 32;
;                 if (actA) sub_tile<MODE>(kf, vf, qfA, oA0, oA1, lA, tau == qtA, offA, fmA, fsp, r, h);
;                 if (actB) sub_tile<MODE>(kf, vf, qfB, oB0, oB1, lB, tau == qtB, offB, fmB, fsp, r, h);
.Lfox_ns1:
	s_and_b64 s[78:79], s[66:67], s[64:65]
	s_cbranch_scc0 .Lfox_nf1
	s_or_b32 s78, s5, 1
	s_cmp_eq_u32 s78, s69
	s_cbranch_scc1 .Lfox_nf1
	s_cmp_eq_u32 s78, s84
	s_cbranch_scc1 .Lfox_nf1
	v_add_u32_e32 v179, s50, v197
	ds_read_b128 v[200:203], v179 offset:18560
	ds_read_b128 v[204:207], v179 offset:18576
	ds_read_b128 v[208:211], v179 offset:18624
	ds_read_b128 v[212:215], v179 offset:18640
	s_waitcnt lgkmcnt(0)
	v_sub_f32_e32 v80, v188, v200
	v_sub_f32_e32 v81, v188, v201
	v_sub_f32_e32 v82, v188, v202
	v_sub_f32_e32 v83, v188, v203
	v_sub_f32_e32 v84, v188, v204
	v_sub_f32_e32 v85, v188, v205
	v_sub_f32_e32 v86, v188, v206
	v_sub_f32_e32 v87, v188, v207
	v_sub_f32_e32 v88, v188, v208
	v_sub_f32_e32 v89, v188, v209
	v_sub_f32_e32 v90, v188, v210
	v_sub_f32_e32 v91, v188, v211
	v_sub_f32_e32 v92, v188, v212
	v_sub_f32_e32 v93, v188, v213
	v_sub_f32_e32 v94, v188, v214
	v_sub_f32_e32 v95, v188, v215
	s_nop 1
	s_setprio 1
	v_mfma_f32_32x32x16_bf16 v[80:95], v[144:147], v[96:99], v[80:95]
	v_mfma_f32_32x32x16_bf16 v[80:95], v[148:151], v[100:103], v[80:95]
	v_mfma_f32_32x32x16_bf16 v[80:95], v[152:155], v[104:107], v[80:95]
	v_mfma_f32_32x32x16_bf16 v[80:95], v[156:159], v[108:111], v[80:95]
	s_setprio 0
	v_sub_f32_e32 v220, v190, v200
	v_sub_f32_e32 v221, v190, v201
	v_sub_f32_e32 v222, v190, v202
	v_sub_f32_e32 v223, v190, v203
	v_sub_f32_e32 v224, v190, v204
	v_sub_f32_e32 v225, v190, v205
	v_sub_f32_e32 v226, v190, v206
	v_sub_f32_e32 v227, v190, v207
	v_sub_f32_e32 v228, v190, v208
	v_sub_f32_e32 v229, v190, v209
	v_sub_f32_e32 v230, v190, v210
	v_sub_f32_e32 v231, v190, v211
	v_sub_f32_e32 v232, v190, v212
	v_sub_f32_e32 v233, v190, v213
	v_sub_f32_e32 v234, v190, v214
	v_sub_f32_e32 v235, v190, v215
	s_nop 1
	s_setprio 1
	v_mfma_f32_32x32x16_bf16 v[220:235], v[144:147], v[112:115], v[220:235]
	v_mfma_f32_32x32x16_bf16 v[220:235], v[148:151], v[116:119], v[220:235]
	v_mfma_f32_32x32x16_bf16 v[220:235], v[152:155], v[120:123], v[220:235]
	v_mfma_f32_32x32x16_bf16 v[220:235], v[156:159], v[124:127], v[220:235]
	s_setprio 0
	v_exp_f32_e32 v80, v80
	v_exp_f32_e32 v81, v81
	v_exp_f32_e32 v82, v82
	v_exp_f32_e32 v83, v83
	v_exp_f32_e32 v84, v84
	v_exp_f32_e32 v85, v85
	v_exp_f32_e32 v86, v86
	v_exp_f32_e32 v87, v87
	v_exp_f32_e32 v88, v88
	v_exp_f32_e32 v89, v89
	v_exp_f32_e32 v90, v90
	v_exp_f32_e32 v91, v91
	v_exp_f32_e32 v92, v92
	v_exp_f32_e32 v93, v93
	v_exp_f32_e32 v94, v94
	v_exp_f32_e32 v95, v95
	v_exp_f32_e32 v220, v220
	v_add_f32_e32 v198, v80, v198
	v_exp_f32_e32 v221, v221
	v_add_f32_e32 v198, v81, v198
	v_exp_f32_e32 v222, v222
	v_add_f32_e32 v198, v82, v198
	v_exp_f32_e32 v223, v223
	v_add_f32_e32 v198, v83, v198
	v_exp_f32_e32 v224, v224
	v_add_f32_e32 v198, v84, v198
	v_exp_f32_e32 v225, v225
	v_add_f32_e32 v198, v85, v198
	v_exp_f32_e32 v226, v226
	v_add_f32_e32 v198, v86, v198
	v_exp_f32_e32 v227, v227
	v_add_f32_e32 v198, v87, v198
	v_exp_f32_e32 v228, v228
	v_add_f32_e32 v198, v88, v198
	v_exp_f32_e32 v229, v229
	v_add_f32_e32 v198, v89, v198
	v_exp_f32_e32 v230, v230
	v_add_f32_e32 v198, v90, v198
	v_exp_f32_e32 v231, v231
	v_add_f32_e32 v198, v91, v198
	v_exp_f32_e32 v232, v232
	v_add_f32_e32 v198, v92, v198
	v_exp_f32_e32 v233, v233
	v_add_f32_e32 v198, v93, v198
	v_exp_f32_e32 v234, v234
	v_add_f32_e32 v198, v94, v198
	v_exp_f32_e32 v235, v235
	v_add_f32_e32 v198, v95, v198
	v_cvt_pk_bf16_f32 v80, v80, v81
	v_cvt_pk_bf16_f32 v81, v82, v83
	v_cvt_pk_bf16_f32 v82, v84, v85
	v_cvt_pk_bf16_f32 v83, v86, v87
	v_cvt_pk_bf16_f32 v84, v88, v89
	v_cvt_pk_bf16_f32 v85, v90, v91
	v_cvt_pk_bf16_f32 v86, v92, v93
	v_cvt_pk_bf16_f32 v87, v94, v95
	s_setprio 1
	v_mfma_f32_32x32x16_bf16 v[64:79], v[140:143], v[80:83], v[64:79]
	v_add_f32_e32 v175, v220, v175
	v_add_f32_e32 v175, v221, v175
	v_add_f32_e32 v175, v222, v175
	v_add_f32_e32 v175, v223, v175
	v_mfma_f32_32x32x16_bf16 v[48:63], v[132:135], v[80:83], v[48:63]
	v_add_f32_e32 v175, v224, v175
	v_add_f32_e32 v175, v225, v175
	v_add_f32_e32 v175, v226, v175
	v_add_f32_e32 v175, v227, v175
	v_mfma_f32_32x32x16_bf16 v[64:79], v[136:139], v[84:87], v[64:79]
	v_add_f32_e32 v175, v228, v175
	v_add_f32_e32 v175, v229, v175
	v_add_f32_e32 v175, v230, v175
	v_add_f32_e32 v175, v231, v175
	v_mfma_f32_32x32x16_bf16 v[48:63], v[128:131], v[84:87], v[48:63]
	v_add_f32_e32 v175, v232, v175
	v_add_f32_e32 v175, v233, v175
	v_add_f32_e32 v175, v234, v175
	v_add_f32_e32 v175, v235, v175
	v_cvt_pk_bf16_f32 v220, v220, v221
	v_cvt_pk_bf16_f32 v221, v222, v223
	v_cvt_pk_bf16_f32 v222, v224, v225
	v_cvt_pk_bf16_f32 v223, v226, v227
	v_cvt_pk_bf16_f32 v224, v228, v229
	v_cvt_pk_bf16_f32 v225, v230, v231
	v_cvt_pk_bf16_f32 v226, v232, v233
	v_cvt_pk_bf16_f32 v227, v234, v235
	v_mfma_f32_32x32x16_bf16 v[32:47], v[140:143], v[220:223], v[32:47]
	v_mfma_f32_32x32x16_bf16 v[16:31], v[132:135], v[220:223], v[16:31]
	v_mfma_f32_32x32x16_bf16 v[32:47], v[136:139], v[224:227], v[32:47]
	v_mfma_f32_32x32x16_bf16 v[16:31], v[128:131], v[224:227], v[16:31]
	s_setprio 0
	s_branch .LBB0_340

; template <int MODE>
; DI void sub_tile(const bf16x8 (&kf)[4], const bf16x8 (&vf)[2][2], const bf16x8 (&qf)[4], f32x16& o0, f32x16& o1, float& l, bool diag, float offs, float fm, const LAS float* fsp, int r, int h) {
;     f32x16 x;
;     float p[16];
;     if (MODE == 2) {
; #pragma unroll
;         for (int i = 0; i < 16; ++i) x[i] = offs;
; #pragma unroll
;         for (int sp = 0; sp < 4; ++sp) x = mfma32(kf[sp], qf[sp], x);
; #pragma unroll
;         for (int i = 0; i < 16; ++i) p[i] = ex2(x[i]);
;     } else {
;         x = qk_tile(kf, qf);
; #pragma unroll
;         for (int g = 0; g < 4; ++g) {
;             const f32x4 fs = *(const LAS f32x4*)(fsp + 16 * (g >> 1) + 8 * h + 4 * (g & 1));
; #pragma unroll
;             for (int e = 0; e < 4; ++e) p[4 * g + e] = ex2(x[4 * g + e] + (fm - fs[e]));
;         }
;     }
;     if (diag) {
; #pragma unroll
;         for (int i = 0; i < 16; ++i) if (kidx(i, h) > r) p[i] = 0.f;
;     }
; #pragma unroll
; template <int MODE>
; DI void attn_wg2_item(const bf16_t* Qm, const bf16_t* Km, const bf16_t* Vtm, const float* Fb, const float* KMPb, const bf16_t* G, bf16_t* Y, int bh, int qb2, int halfq, int mixer, float Mb, LAS unsigned char* lds, int tid, int wave, int lane) {
;     ...
;             const int tau = cur * 2 + kk, nb = tau >> 3;
;             bool actA = tau <= qtA, actB = tau <= qtB;
;             if (MODE == 2) { actA = actA && ((visA >> nb) & 1u); actB = actB && ((visB >> nb) & 1u); }
;             if (actA || actB) {
;                 bf16x8 kf[4], vf[2][2];
; #pragma unroll
;                 for (int sp = 0; sp < 4; ++sp) kf[sp] = *(LAS bf16x8*)(lb + kra + kk * 32 * 144 + sp * 32);
; #pragma unroll
;                 for (int dd = 0; dd < 2; ++dd)
; #pragma unroll
;                     for (int s = 0; s < 2; ++s) vf[dd][s] = *(LAS bf16x8*)(lb + vra + dd * 32 * 144 + kk * 64 + s * 32);
;                 float offA = mb2, offB = mb2;
;                 if (MODE == 2) { offA = ((nb == qblkA) || ((selA >> nb) & 1u)) ? mb2 : NEGI; offB = ((nb == qblkB) || ((selB >> nb) & 1u)) ? mb2 : NEGI; }
;                 const LAS float* fsp = (const LAS float*)(lb + AW_F) + kk * 32;
;                 if (actA) sub_tile<MODE>(kf, vf, qfA, oA0, oA1, lA, tau == qtA, offA, fmA, fsp, r, h);
;                 if (actB) sub_tile<MODE>(kf, vf, qfB, oB0, oB1, lB, tau == qtB, offB, fmB, fsp, r, h);
;             }
.LBB0_393:
	s_mul_i32 s47, s79, 0x4900
	s_add_i32 s47, s47, 0
	s_lshl_b32 s87, s46, 1
	s_lshr_b32 s88, s46, 2
	s_cmp_lt_i32 s87, s84
	v_add_u32_e32 v0, s47, v175
	v_add_u32_e32 v10, s47, v173
	s_cselect_b64 s[46:47], -1, 0
	s_cmp_lt_i32 s87, s85
	s_cselect_b64 s[64:65], -1, 0
	s_lshl_b32 s89, 1, s88
	v_and_b32_e32 v11, s89, v176
	v_cmp_ne_u32_e32 vcc, 0, v11
	v_and_b32_e32 v11, s89, v177
	s_and_b64 s[48:49], s[46:47], vcc
	v_cmp_ne_u32_e64 s[46:47], 0, v11
	s_and_b64 s[66:67], s[64:65], s[46:47]
	s_or_b64 s[68:69], s[48:49], s[66:67]
	v_add_u32_e32 v14, v0, v172
	v_add_u32_e32 v0, v10, v172
	s_and_saveexec_b64 s[64:65], s[68:69]
	s_cbranch_execz .LBB0_403
	ds_read_b128 v[152:155], v14 offset:4608
	ds_read_b128 v[148:151], v14 offset:4640
	ds_read_b128 v[144:147], v14 offset:4672
	ds_read_b128 v[140:143], v14 offset:4704
	ds_read_b128 v[136:139], v0 offset:9280
	ds_read_b128 v[132:135], v0 offset:9312
	ds_read_b128 v[128:131], v0 offset:13888
	ds_read_b128 v[10:13], v0 offset:13920
	s_or_b32 s90, s87, 1
	s_cmp_lt_i32 s85, 0
	s_cbranch_scc0 .Lmoba_ns1
	s_and_b64 s[92:93], s[48:49], exec
	s_cbranch_scc0 .Lmoba_ns1
	s_cmp_lt_i32 s90, s84
	s_cbranch_scc0 .Lmoba_ns1
	ds_read_b128 v[212:215], v0 offset:9216
	ds_read_b128 v[216:219], v0 offset:9248
	ds_read_b128 v[220:223], v0 offset:13824
	ds_read_b128 v[224:227], v0 offset:13856
	s_waitcnt lgkmcnt(8)
	s_setprio 1
	v_mfma_f32_32x32x16_bf16 v[80:95], v[152:155], v[96:99], v[196:211]
	v_mfma_f32_32x32x16_bf16 v[80:95], v[148:151], v[100:103], v[80:95]
	v_mfma_f32_32x32x16_bf16 v[80:95], v[144:147], v[104:107], v[80:95]
	v_mfma_f32_32x32x16_bf16 v[80:95], v[140:143], v[108:111], v[80:95]
	s_setprio 0
	s_nop 7
	ds_read_b128 v[152:155], v14
	ds_read_b128 v[148:151], v14 offset:32
	ds_read_b128 v[144:147], v14 offset:64
	ds_read_b128 v[140:143], v14 offset:96
	v_exp_f32_e32 v80, v80
	v_exp_f32_e32 v81, v81
	v_exp_f32_e32 v82, v82
	v_exp_f32_e32 v83, v83
	v_exp_f32_e32 v84, v84
	v_exp_f32_e32 v85, v85
	v_exp_f32_e32 v86, v86
	v_exp_f32_e32 v87, v87
	v_exp_f32_e32 v88, v88
	v_exp_f32_e32 v89, v89
	v_exp_f32_e32 v90, v90
	v_exp_f32_e32 v91, v91
	v_exp_f32_e32 v92, v92
	v_exp_f32_e32 v93, v93
	v_exp_f32_e32 v94, v94
	v_exp_f32_e32 v95, v95
	s_waitcnt lgkmcnt(0)
	s_setprio 1
	v_mfma_f32_32x32x16_bf16 v[228:243], v[152:155], v[96:99], v[196:211]
	v_mfma_f32_32x32x16_bf16 v[228:243], v[148:151], v[100:103], v[228:243]
	v_mfma_f32_32x32x16_bf16 v[228:243], v[144:147], v[104:107], v[228:243]
	v_mfma_f32_32x32x16_bf16 v[228:243], v[140:143], v[108:111], v[228:243]
	s_setprio 0
	v_add_f32_e32 v186, v80, v186
	v_add_f32_e32 v186, v81, v186
	v_add_f32_e32 v186, v82, v186
	v_add_f32_e32 v186, v83, v186
	v_add_f32_e32 v186, v84, v186
	v_add_f32_e32 v186, v85, v186
	v_add_f32_e32 v186, v86, v186
	v_add_f32_e32 v186, v87, v186
	v_add_f32_e32 v186, v88, v186
	v_add_f32_e32 v186, v89, v186
	v_add_f32_e32 v186, v90, v186
	v_add_f32_e32 v186, v91, v186
	v_add_f32_e32 v186, v92, v186
	v_add_f32_e32 v186, v93, v186
	v_add_f32_e32 v186, v94, v186
	v_add_f32_e32 v186, v95, v186
	v_cvt_pk_bf16_f32 v80, v80, v81
	v_cvt_pk_bf16_f32 v81, v82, v83
	v_cvt_pk_bf16_f32 v82, v84, v85
	v_cvt_pk_bf16_f32 v83, v86, v87
	v_cvt_pk_bf16_f32 v84, v88, v89
	v_cvt_pk_bf16_f32 v85, v90, v91
	v_cvt_pk_bf16_f32 v86, v92, v93
	v_cvt_pk_bf16_f32 v87, v94, v95
	s_setprio 1
	v_mfma_f32_32x32x16_bf16 v[64:79], v[136:139], v[80:83], v[64:79]
	v_exp_f32_e32 v228, v228
	v_exp_f32_e32 v229, v229
	v_exp_f32_e32 v230, v230
	v_exp_f32_e32 v231, v231
	v_mfma_f32_32x32x16_bf16 v[48:63], v[128:131], v[80:83], v[48:63]
	v_exp_f32_e32 v232, v232
	v_exp_f32_e32 v233, v233
	v_exp_f32_e32 v234, v234
	v_exp_f32_e32 v235, v235
	v_mfma_f32_32x32x16_bf16 v[64:79], v[132:135], v[84:87], v[64:79]
	v_exp_f32_e32 v236, v236
	v_exp_f32_e32 v237, v237
	v_exp_f32_e32 v238, v238
	v_exp_f32_e32 v239, v239
	v_mfma_f32_32x32x16_bf16 v[48:63], v[10:13], v[84:87], v[48:63]
	v_exp_f32_e32 v240, v240
	v_exp_f32_e32 v241, v241
	v_exp_f32_e32 v242, v242
	v_exp_f32_e32 v243, v243
	s_setprio 0
	v_add_f32_e32 v186, v228, v186
	v_add_f32_e32 v186, v229, v186
	v_add_f32_e32 v186, v230, v186
	v_add_f32_e32 v186, v231, v186
	v_add_f32_e32 v186, v232, v186
	v_add_f32_e32 v186, v233, v186
	v_add_f32_e32 v186, v234, v186
	v_add_f32_e32 v186, v235, v186
	v_add_f32_e32 v186, v236, v186
	v_add_f32_e32 v186, v237, v186
	v_add_f32_e32 v186, v238, v186
	v_add_f32_e32 v186, v239, v186
	v_add_f32_e32 v186, v240, v186
	v_add_f32_e32 v186, v241, v186
	v_add_f32_e32 v186, v242, v186
	v_add_f32_e32 v186, v243, v186
	v_cvt_pk_bf16_f32 v228, v228, v229
	v_cvt_pk_bf16_f32 v229, v230, v231
	v_cvt_pk_bf16_f32 v230, v232, v233
	v_cvt_pk_bf16_f32 v231, v234, v235
	v_cvt_pk_bf16_f32 v232, v236, v237
	v_cvt_pk_bf16_f32 v233, v238, v239
	v_cvt_pk_bf16_f32 v234, v240, v241
	v_cvt_pk_bf16_f32 v235, v242, v243
	s_setprio 1
	v_mfma_f32_32x32x16_bf16 v[64:79], v[212:215], v[228:231], v[64:79]
	v_mfma_f32_32x32x16_bf16 v[48:63], v[220:223], v[228:231], v[48:63]
	v_mfma_f32_32x32x16_bf16 v[64:79], v[216:219], v[232:235], v[64:79]
	v_mfma_f32_32x32x16_bf16 v[48:63], v[224:227], v[232:235], v[48:63]
	s_setprio 0
	s_branch .LBB0_413
; #define LAS __attribute__((address_space(3)))
; DI f32x16 mfma32(bf16x8 a, bf16x8 b, f32x16 c) { return __builtin_amdgcn_mfma_f32_32x32x16_bf16(a, b, c, 0, 0, 0); }
; DI float ex2(float x) { return __builtin_amdgcn_exp2f(x); }
; template <int MODE>
; DI void sub_tile(const bf16x8 (&kf)[4], const bf16x8 (&vf)[2][2], const bf16x8 (&qf)[4], f32x16& o0, f32x16& o1, float& l, bool diag, float offs, float fm, const LAS float* fsp, int r, int h) {
;     f32x16 x;
;     float p[16];
;     if (MODE == 2) {
; #pragma unroll
;         for (int i = 0; i < 16; ++i) x[i] = offs;
; #pragma unroll
;         for (int sp = 0; sp < 4; ++sp) x = mfma32(kf[sp], qf[sp], x);
; #pragma unroll
;         for (int i = 0; i < 16; ++i) p[i] = ex2(x[i]);
;     } else {
;         x = qk_tile(kf, qf);
; #pragma unroll
;         for (int g = 0; g < 4; ++g) {
;             const f32x4 fs = *(const LAS f32x4*)(fsp + 16 * (g >> 1) + 8 * h + 4 * (g & 1));
; #pragma unroll
;             for (int e = 0; e < 4; ++e) p[4 * g + e] = ex2(x[4 * g + e] + (fm - fs[e]));
;         }
;     }
;     if (diag) {
; #pragma unroll
;         for (int i = 0; i < 16; ++i) if (kidx(i, h) > r) p[i] = 0.f;
;     }
; #pragma unroll
;     for (int i = 0; i < 16; ++i) l += p[i];
;     pv_tile(o0, o1, vf, p);
; }
; template <int MODE>
; DI void attn_wg2_item(const bf16_t* Qm, const bf16_t* Km, const bf16_t* Vtm, const float* Fb, const float* KMPb, const bf16_t* G, bf16_t* Y, int bh, int qb2, int halfq, int mixer, float Mb, LAS unsigned char* lds, int tid, int wave, int lane) {
;     ...
;                 float offA = mb2, offB = mb2;
;                 if (MODE == 2) { offA = ((nb == qblkA) || ((selA >> nb) & 1u)) ? mb2 : NEGI; offB = ((nb == qblkB) || ((selB >> nb) & 1u)) ? mb2 : NEGI; }
;                 const LAS float* fsp = (const LAS float*)(lb + AW_F) + kk * 32;
;                 if (actA) sub_tile<MODE>(kf, vf, qfA, oA0, oA1, lA, tau == qtA, offA, fmA, fsp, r, h);
;                 if (actB) sub_tile<MODE>(kf, vf, qfB, oB0, oB1, lB, tau == qtB, offB, fmB, fsp, r, h);
.Lmoba_ns1:
	s_and_b64 s[92:93], s[48:49], s[66:67]
	s_cbranch_scc0 .Lmoba_nf1
	s_cmp_eq_u32 s90, s84
	s_cbranch_scc1 .Lmoba_nf1
	s_cmp_eq_u32 s90, s85
	s_cbranch_scc1 .Lmoba_nf1
	s_waitcnt lgkmcnt(4)
	s_setprio 1
	v_mfma_f32_32x32x16_bf16 v[80:95], v[152:155], v[96:99], v[196:211]
	v_mfma_f32_32x32x16_bf16 v[80:95], v[148:151], v[100:103], v[80:95]
	v_mfma_f32_32x32x16_bf16 v[80:95], v[144:147], v[104:107], v[80:95]
	v_mfma_f32_32x32x16_bf16 v[80:95], v[140:143], v[108:111], v[80:95]
	v_mfma_f32_32x32x16_bf16 v[228:243], v[152:155], v[112:115], v[212:227]
	v_mfma_f32_32x32x16_bf16 v[228:243], v[148:151], v[116:119], v[228:243]
	v_mfma_f32_32x32x16_bf16 v[228:243], v[144:147], v[120:123], v[228:243]
	v_mfma_f32_32x32x16_bf16 v[228:243], v[140:143], v[124:127], v[228:243]
	s_setprio 0
	s_nop 6
	v_exp_f32_e32 v80, v80
	v_exp_f32_e32 v81, v81
	v_exp_f32_e32 v82, v82
	v_exp_f32_e32 v83, v83
	v_exp_f32_e32 v84, v84
	v_exp_f32_e32 v85, v85
	v_exp_f32_e32 v86, v86
	v_exp_f32_e32 v87, v87
	v_exp_f32_e32 v88, v88
	v_exp_f32_e32 v89, v89
	v_exp_f32_e32 v90, v90
	v_exp_f32_e32 v91, v91
	v_exp_f32_e32 v92, v92
	v_exp_f32_e32 v93, v93
	v_exp_f32_e32 v94, v94
	v_exp_f32_e32 v95, v95
	v_exp_f32_e32 v228, v228
	v_add_f32_e32 v186, v80, v186
	v_exp_f32_e32 v229, v229
	v_add_f32_e32 v186, v81, v186
	v_exp_f32_e32 v230, v230
	v_add_f32_e32 v186, v82, v186
	v_exp_f32_e32 v231, v231
	v_add_f32_e32 v186, v83, v186
	v_exp_f32_e32 v232, v232
	v_add_f32_e32 v186, v84, v186
	v_exp_f32_e32 v233, v233
	v_add_f32_e32 v186, v85, v186
	v_exp_f32_e32 v234, v234
	v_add_f32_e32 v186, v86, v186
	v_exp_f32_e32 v235, v235
	v_add_f32_e32 v186, v87, v186
	v_exp_f32_e32 v236, v236
	v_add_f32_e32 v186, v88, v186
	v_exp_f32_e32 v237, v237
	v_add_f32_e32 v186, v89, v186
	v_exp_f32_e32 v238, v238
	v_add_f32_e32 v186, v90, v186
	v_exp_f32_e32 v239, v239
	v_add_f32_e32 v186, v91, v186
	v_exp_f32_e32 v240, v240
	v_add_f32_e32 v186, v92, v186
	v_exp_f32_e32 v241, v241
	v_add_f32_e32 v186, v93, v186
	v_exp_f32_e32 v242, v242
	v_add_f32_e32 v186, v94, v186
	v_exp_f32_e32 v243, v243
	v_add_f32_e32 v186, v95, v186
	s_waitcnt lgkmcnt(0)
	v_cvt_pk_bf16_f32 v80, v80, v81
	v_cvt_pk_bf16_f32 v81, v82, v83
	v_cvt_pk_bf16_f32 v82, v84, v85
	v_cvt_pk_bf16_f32 v83, v86, v87
	v_cvt_pk_bf16_f32 v84, v88, v89
	v_cvt_pk_bf16_f32 v85, v90, v91
	v_cvt_pk_bf16_f32 v86, v92, v93
	v_cvt_pk_bf16_f32 v87, v94, v95
	s_setprio 1
	v_mfma_f32_32x32x16_bf16 v[64:79], v[136:139], v[80:83], v[64:79]
	v_add_f32_e32 v170, v228, v170
	v_add_f32_e32 v170, v229, v170
	v_add_f32_e32 v170, v230, v170
	v_add_f32_e32 v170, v231, v170
	v_mfma_f32_32x32x16_bf16 v[48:63], v[128:131], v[80:83], v[48:63]
	v_add_f32_e32 v170, v232, v170
	v_add_f32_e32 v170, v233, v170
	v_add_f32_e32 v170, v234, v170
	v_add_f32_e32 v170, v235, v170
	v_mfma_f32_32x32x16_bf16 v[64:79], v[132:135], v[84:87], v[64:79]
	v_add_f32_e32 v170, v236, v170
	v_add_f32_e32 v170, v237, v170
	v_add_f32_e32 v170, v238, v170
	v_add_f32_e32 v170, v239, v170
	v_mfma_f32_32x32x16_bf16 v[48:63], v[10:13], v[84:87], v[48:63]
	v_add_f32_e32 v170, v240, v170
	v_add_f32_e32 v170, v241, v170
	v_add_f32_e32 v170, v242, v170
	v_add_f32_e32 v170, v243, v170
	v_cvt_pk_bf16_f32 v228, v228, v229
	v_cvt_pk_bf16_f32 v229, v230, v231
	v_cvt_pk_bf16_f32 v230, v232, v233
	v_cvt_pk_bf16_f32 v231, v234, v235
	v_cvt_pk_bf16_f32 v232, v236, v237
	v_cvt_pk_bf16_f32 v233, v238, v239
	v_cvt_pk_bf16_f32 v234, v240, v241
	v_cvt_pk_bf16_f32 v235, v242, v243
	v_mfma_f32_32x32x16_bf16 v[32:47], v[136:139], v[228:231], v[32:47]
	v_mfma_f32_32x32x16_bf16 v[16:31], v[128:131], v[228:231], v[16:31]
	v_mfma_f32_32x32x16_bf16 v[32:47], v[132:135], v[232:235], v[32:47]
	v_mfma_f32_32x32x16_bf16 v[16:31], v[10:13], v[232:235], v[16:31]
	s_setprio 0
	s_branch .LBB0_403
